# DSA attention VALU trim (bfe+bfi masks, max3 chain, packed sub), silu staging batched, DSA indexer key-tile loop software-pipelined
# speedup vs baseline: 1.0621x; 1.0003x over previous
.LBB0_5:
	s_or_b64 exec, exec, s[0:1]
	s_movk_i32 s0, 0x2000
	s_lshr_b32 s25, s22, 6
	v_cmp_gt_i32_e32 vcc, s0, v2
	buffer_wbl2 sc1
	s_waitcnt vmcnt(0) lgkmcnt(0)
	buffer_inv sc1
	s_barrier
	s_and_saveexec_b64 s[0:1], vcc
	s_cbranch_execz .LBB0_8
	v_mov_b32_e32 v3, 0xf000
	global_load_dwordx2 v[4:5], v3, s[46:47] offset:8
	s_lshl_b32 s2, s25, 8
	s_add_i32 s2, s2, 16
	v_lshl_add_u32 v3, v192, 2, s2
	v_readlane_b32 s2, v252, 2
	v_mov_b32_e32 v193, 0
	v_readlane_b32 s3, v252, 3
	s_mov_b32 s4, s2
	s_ashr_i32 s5, s2, 31
	v_writelane_b32 v252, s2, 2
	v_lshl_add_u64 v[6:7], v[192:193], 0, s[4:5]
	v_add_u32_e32 v3, 0x11170, v3
	v_add_u32_e32 v8, 0xfffffe00, v2
	v_writelane_b32 v252, s3, 3
	v_lshlrev_b64 v[6:7], 2, v[6:7]
	s_mov_b64 s[2:3], 0
	s_mov_b64 s[4:5], 0x800
	s_movk_i32 s6, 0x1dff
	s_waitcnt vmcnt(0)
	v_readfirstlane_b32 s8, v4
	v_readfirstlane_b32 s9, v5
	s_nop 1
	v_lshl_add_u64 v[10:11], s[8:9], 0, v[6:7]
	global_load_dword v12, v[10:11], off
	global_load_dword v13, v[10:11], off offset:2048
	v_add_co_u32_e32 v10, vcc, 0x1000, v10
	s_nop 1
	v_addc_co_u32_e32 v11, vcc, 0, v11, vcc
	global_load_dword v14, v[10:11], off
	global_load_dword v15, v[10:11], off offset:2048
	v_add_co_u32_e32 v10, vcc, 0x1000, v10
	s_nop 1
	v_addc_co_u32_e32 v11, vcc, 0, v11, vcc
	global_load_dword v16, v[10:11], off
	global_load_dword v17, v[10:11], off offset:2048
	v_add_co_u32_e32 v10, vcc, 0x1000, v10
	s_nop 1
	v_addc_co_u32_e32 v11, vcc, 0, v11, vcc
	global_load_dword v18, v[10:11], off
	global_load_dword v19, v[10:11], off offset:2048
	v_add_co_u32_e32 v10, vcc, 0x1000, v10
	s_nop 1
	v_addc_co_u32_e32 v11, vcc, 0, v11, vcc
	global_load_dword v20, v[10:11], off
	global_load_dword v21, v[10:11], off offset:2048
	v_add_co_u32_e32 v10, vcc, 0x1000, v10
	s_nop 1
	v_addc_co_u32_e32 v11, vcc, 0, v11, vcc
	global_load_dword v22, v[10:11], off
	global_load_dword v23, v[10:11], off offset:2048
	v_add_co_u32_e32 v10, vcc, 0x1000, v10
	s_nop 1
	v_addc_co_u32_e32 v11, vcc, 0, v11, vcc
	global_load_dword v24, v[10:11], off
	global_load_dword v25, v[10:11], off offset:2048
	v_add_co_u32_e32 v10, vcc, 0x1000, v10
	s_nop 1
	v_addc_co_u32_e32 v11, vcc, 0, v11, vcc
	global_load_dword v26, v[10:11], off
	global_load_dword v27, v[10:11], off offset:2048
	s_waitcnt vmcnt(14)
	v_mul_f32_e32 v6, 0xbfb8aa3b, v12
	v_mul_f32_e32 v7, 0xbfb8aa3b, v13
	v_exp_f32_e32 v6, v6
	v_exp_f32_e32 v7, v7
	s_nop 0
	v_add_f32_e32 v6, 1.0, v6
	v_add_f32_e32 v7, 1.0, v7
	v_rcp_f32_e32 v6, v6
	v_rcp_f32_e32 v7, v7
	s_nop 0
	v_mul_f32_e32 v12, v12, v6
	v_mul_f32_e32 v13, v13, v7
	ds_write_b32 v3, v12
	ds_write_b32 v3, v13 offset:2048
	s_waitcnt vmcnt(12)
	v_mul_f32_e32 v6, 0xbfb8aa3b, v14
	v_mul_f32_e32 v7, 0xbfb8aa3b, v15
	v_exp_f32_e32 v6, v6
	v_exp_f32_e32 v7, v7
	s_nop 0
	v_add_f32_e32 v6, 1.0, v6
	v_add_f32_e32 v7, 1.0, v7
	v_rcp_f32_e32 v6, v6
	v_rcp_f32_e32 v7, v7
	s_nop 0
	v_mul_f32_e32 v14, v14, v6
	v_mul_f32_e32 v15, v15, v7
	ds_write_b32 v3, v14 offset:4096
	ds_write_b32 v3, v15 offset:6144
	s_waitcnt vmcnt(10)
	v_mul_f32_e32 v6, 0xbfb8aa3b, v16
	v_mul_f32_e32 v7, 0xbfb8aa3b, v17
	v_exp_f32_e32 v6, v6
	v_exp_f32_e32 v7, v7
	s_nop 0
	v_add_f32_e32 v6, 1.0, v6
	v_add_f32_e32 v7, 1.0, v7
	v_rcp_f32_e32 v6, v6
	v_rcp_f32_e32 v7, v7
	s_nop 0
	v_mul_f32_e32 v16, v16, v6
	v_mul_f32_e32 v17, v17, v7
	ds_write_b32 v3, v16 offset:8192
	ds_write_b32 v3, v17 offset:10240
	s_waitcnt vmcnt(8)
	v_mul_f32_e32 v6, 0xbfb8aa3b, v18
	v_mul_f32_e32 v7, 0xbfb8aa3b, v19
	v_exp_f32_e32 v6, v6
	v_exp_f32_e32 v7, v7
	s_nop 0
	v_add_f32_e32 v6, 1.0, v6
	v_add_f32_e32 v7, 1.0, v7
	v_rcp_f32_e32 v6, v6
	v_rcp_f32_e32 v7, v7
	s_nop 0
	v_mul_f32_e32 v18, v18, v6
	v_mul_f32_e32 v19, v19, v7
	ds_write_b32 v3, v18 offset:12288
	ds_write_b32 v3, v19 offset:14336
	s_waitcnt vmcnt(6)
	v_mul_f32_e32 v6, 0xbfb8aa3b, v20
	v_mul_f32_e32 v7, 0xbfb8aa3b, v21
	v_exp_f32_e32 v6, v6
	v_exp_f32_e32 v7, v7
	s_nop 0
	v_add_f32_e32 v6, 1.0, v6
	v_add_f32_e32 v7, 1.0, v7
	v_rcp_f32_e32 v6, v6
	v_rcp_f32_e32 v7, v7
	s_nop 0
	v_mul_f32_e32 v20, v20, v6
	v_mul_f32_e32 v21, v21, v7
	ds_write_b32 v3, v20 offset:16384
	ds_write_b32 v3, v21 offset:18432
	s_waitcnt vmcnt(4)
	v_mul_f32_e32 v6, 0xbfb8aa3b, v22
	v_mul_f32_e32 v7, 0xbfb8aa3b, v23
	v_exp_f32_e32 v6, v6
	v_exp_f32_e32 v7, v7
	s_nop 0
	v_add_f32_e32 v6, 1.0, v6
	v_add_f32_e32 v7, 1.0, v7
	v_rcp_f32_e32 v6, v6
	v_rcp_f32_e32 v7, v7
	s_nop 0
	v_mul_f32_e32 v22, v22, v6
	v_mul_f32_e32 v23, v23, v7
	ds_write_b32 v3, v22 offset:20480
	ds_write_b32 v3, v23 offset:22528
	s_waitcnt vmcnt(2)
	v_mul_f32_e32 v6, 0xbfb8aa3b, v24
	v_mul_f32_e32 v7, 0xbfb8aa3b, v25
	v_exp_f32_e32 v6, v6
	v_exp_f32_e32 v7, v7
	s_nop 0
	v_add_f32_e32 v6, 1.0, v6
	v_add_f32_e32 v7, 1.0, v7
	v_rcp_f32_e32 v6, v6
	v_rcp_f32_e32 v7, v7
	s_nop 0
	v_mul_f32_e32 v24, v24, v6
	v_mul_f32_e32 v25, v25, v7
	ds_write_b32 v3, v24 offset:24576
	ds_write_b32 v3, v25 offset:26624
	s_waitcnt vmcnt(0)
	v_mul_f32_e32 v6, 0xbfb8aa3b, v26
	v_mul_f32_e32 v7, 0xbfb8aa3b, v27
	v_exp_f32_e32 v6, v6
	v_exp_f32_e32 v7, v7
	s_nop 0
	v_add_f32_e32 v6, 1.0, v6
	v_add_f32_e32 v7, 1.0, v7
	v_rcp_f32_e32 v6, v6
	v_rcp_f32_e32 v7, v7
	s_nop 0
	v_mul_f32_e32 v26, v26, v6
	v_mul_f32_e32 v27, v27, v7
	ds_write_b32 v3, v26 offset:28672
	ds_write_b32 v3, v27 offset:30720

.LBB0_375:
	s_or_b64 exec, exec, s[0:1]
	s_waitcnt lgkmcnt(0)
	s_barrier
	ds_read_b32 v0, v195 offset:8
	s_movk_i32 s0, 0x587
	s_waitcnt lgkmcnt(0)
	v_cmp_lt_i32_e64 s[82:83], s0, v0
	v_readfirstlane_b32 s72, v0
	s_and_b64 vcc, exec, s[82:83]
	s_cbranch_vccnz .LBB0_370
	v_readlane_b32 s0, v252, 2
	v_mov_b32_e32 v94, v192
	v_readlane_b32 s1, v252, 3
	s_cmp_gt_i32 s72, 7
	v_readfirstlane_b32 s6, v4
	v_readfirstlane_b32 s7, v5
	v_readfirstlane_b32 s86, v2
	v_readfirstlane_b32 s87, v3
	v_add_u32_e32 v128, s0, v94
	s_mov_b64 s[0:1], -1
	s_cbranch_scc0 .LBB0_1130
	s_cmpk_gt_u32 s72, 0x187
	s_cbranch_scc0 .LBB0_867
	s_sub_i32 s0, 0x587, s72
	s_lshr_b32 s95, s0, 7
	s_lshl_b32 s0, s0, 4
	s_and_b32 s94, s0, 0x7f0
	s_add_u32 s0, s6, 0x1200000
	s_addc_u32 s1, s7, 0
	v_writelane_b32 v254, s0, 39
	s_cmpk_gt_u32 s94, 0xff
	s_nop 0
	v_writelane_b32 v254, s1, 40
	s_mov_b64 s[0:1], -1
	s_cbranch_scc0 .LBB0_855
	s_lshl_b32 s0, s95, 11
	s_lshr_b32 s4, s94, 5
	v_readlane_b32 s11, v253, 45
	v_writelane_b32 v254, s0, 41
	s_cmp_gt_u32 s11, s4
	s_cbranch_scc1 .LBB0_386
	s_add_u32 s0, s6, 0x8200000
	v_readlane_b32 s5, v254, 41
	s_addc_u32 s1, s7, 0
	s_or_b32 s5, s5, s94
	v_bfe_u32 v8, v94, 2, 3
	v_or_b32_e32 v2, s5, v8
	v_ashrrev_i32_e32 v7, 5, v94
	v_mul_u32_u24_e32 v2, 0xd00, v2
	v_lshlrev_b32_e32 v0, 3, v7
	v_lshlrev_b32_e32 v194, 1, v2
	v_lshlrev_b32_e32 v4, 7, v94
	v_ashrrev_i32_e32 v1, 31, v0
	v_lshl_add_u64 v[2:3], s[0:1], 0, v[194:195]
	v_and_b32_e32 v194, 0x180, v4
	v_lshl_add_u64 v[2:3], v[2:3], 0, v[194:195]
	v_lshlrev_b64 v[0:1], 1, v[0:1]
	v_lshl_add_u64 v[2:3], v[2:3], 0, v[0:1]
	global_load_dwordx4 v[32:35], v[2:3], off offset:768
	global_load_dwordx4 v[36:39], v[2:3], off offset:800
	global_load_dwordx4 v[40:43], v[2:3], off offset:832
	global_load_dwordx4 v[44:47], v[2:3], off offset:864
	v_add_u32_e32 v9, s5, v7
	v_mov_b64_e32 v[2:3], s[0:1]
	s_movk_i32 s10, 0x1a00
	s_or_b32 s5, s5, 8
	v_and_b32_e32 v6, 31, v94
	v_or_b32_e32 v4, s5, v8
	v_mul_u32_u24_e32 v4, 0xd00, v4
	v_lshlrev_b32_e32 v4, 1, v4
	v_mov_b32_e32 v5, v195
	v_lshl_add_u64 v[4:5], s[0:1], 0, v[4:5]
	v_lshl_add_u64 v[4:5], v[4:5], 0, v[194:195]
	v_lshl_add_u64 v[4:5], v[4:5], 0, v[0:1]
	v_add_u32_e32 v8, s5, v7
	global_load_dwordx4 v[48:51], v[4:5], off offset:768
	global_load_dwordx4 v[52:55], v[4:5], off offset:800
	global_load_dwordx4 v[56:59], v[4:5], off offset:832
	global_load_dwordx4 v[60:63], v[4:5], off offset:864
	v_mad_i64_i32 v[64:65], s[8:9], v9, s10, v[2:3]
	v_add_u32_e32 v4, 2, v9
	v_mad_i64_i32 v[66:67], s[8:9], v4, s10, v[2:3]
	v_add_u32_e32 v4, 4, v9
	v_mad_i64_i32 v[68:69], s[8:9], v4, s10, v[2:3]
	v_add_u32_e32 v4, 6, v9
	v_mad_i64_i32 v[70:71], s[8:9], v4, s10, v[2:3]
	v_mad_i64_i32 v[72:73], s[8:9], v8, s10, v[2:3]
	v_add_u32_e32 v4, 2, v8
	v_mad_i64_i32 v[74:75], s[8:9], v4, s10, v[2:3]
	v_add_u32_e32 v4, 4, v8
	v_mad_i64_i32 v[76:77], s[8:9], v4, s10, v[2:3]
	v_add_u32_e32 v4, 6, v8
	v_mad_i64_i32 v[78:79], s[8:9], v4, s10, v[2:3]
	global_load_dwordx2 v[64:65], v[64:65], off offset:1408
	global_load_dwordx2 v[66:67], v[66:67], off offset:1408
	global_load_dwordx2 v[68:69], v[68:69], off offset:1408
	global_load_dwordx2 v[70:71], v[70:71], off offset:1408
	global_load_dwordx2 v[72:73], v[72:73], off offset:1408
	global_load_dwordx2 v[74:75], v[74:75], off offset:1408
	global_load_dwordx2 v[76:77], v[76:77], off offset:1408
	global_load_dwordx2 v[78:79], v[78:79], off offset:1408
	s_mov_b32 s8, s11
	s_add_i32 s5, s4, -8
	v_add_u32_e32 v194, s33, v6
	s_movk_i32 s0, 0x2020
	s_waitcnt vmcnt(0)
	v_cvt_f32_f16_e32 v95, v64
	v_cvt_f32_f16_sdwa v96, v64 dst_sel:DWORD dst_unused:UNUSED_PAD src0_sel:WORD_1
	v_cvt_f32_f16_e32 v97, v65
	v_cvt_f32_f16_sdwa v98, v65 dst_sel:DWORD dst_unused:UNUSED_PAD src0_sel:WORD_1
	v_cvt_f32_f16_e32 v99, v66
	v_cvt_f32_f16_sdwa v100, v66 dst_sel:DWORD dst_unused:UNUSED_PAD src0_sel:WORD_1
	v_cvt_f32_f16_e32 v101, v67
	v_cvt_f32_f16_sdwa v102, v67 dst_sel:DWORD dst_unused:UNUSED_PAD src0_sel:WORD_1
	v_cvt_f32_f16_e32 v103, v68
	v_cvt_f32_f16_sdwa v104, v68 dst_sel:DWORD dst_unused:UNUSED_PAD src0_sel:WORD_1
	v_cvt_f32_f16_e32 v105, v69
	v_cvt_f32_f16_sdwa v106, v69 dst_sel:DWORD dst_unused:UNUSED_PAD src0_sel:WORD_1
	v_cvt_f32_f16_e32 v107, v70
	v_cvt_f32_f16_sdwa v108, v70 dst_sel:DWORD dst_unused:UNUSED_PAD src0_sel:WORD_1
	v_cvt_f32_f16_e32 v109, v71
	v_cvt_f32_f16_sdwa v110, v71 dst_sel:DWORD dst_unused:UNUSED_PAD src0_sel:WORD_1
	v_cvt_f32_f16_e32 v111, v72
	v_cvt_f32_f16_sdwa v112, v72 dst_sel:DWORD dst_unused:UNUSED_PAD src0_sel:WORD_1
	v_cvt_f32_f16_e32 v113, v73
	v_cvt_f32_f16_sdwa v114, v73 dst_sel:DWORD dst_unused:UNUSED_PAD src0_sel:WORD_1
	v_cvt_f32_f16_e32 v115, v74
	v_cvt_f32_f16_sdwa v116, v74 dst_sel:DWORD dst_unused:UNUSED_PAD src0_sel:WORD_1
	v_cvt_f32_f16_e32 v117, v75
	v_cvt_f32_f16_sdwa v118, v75 dst_sel:DWORD dst_unused:UNUSED_PAD src0_sel:WORD_1
	v_cvt_f32_f16_e32 v119, v76
	v_cvt_f32_f16_sdwa v120, v76 dst_sel:DWORD dst_unused:UNUSED_PAD src0_sel:WORD_1
	v_cvt_f32_f16_e32 v121, v77
	v_cvt_f32_f16_sdwa v122, v77 dst_sel:DWORD dst_unused:UNUSED_PAD src0_sel:WORD_1
	v_cvt_f32_f16_e32 v123, v78
	v_cvt_f32_f16_sdwa v124, v78 dst_sel:DWORD dst_unused:UNUSED_PAD src0_sel:WORD_1
	v_cvt_f32_f16_e32 v125, v79
	v_cvt_f32_f16_sdwa v126, v79 dst_sel:DWORD dst_unused:UNUSED_PAD src0_sel:WORD_1
	v_mul_lo_u32 v2, v7, s0
	v_lshlrev_b32_e32 v3, 2, v6
	v_readlane_b32 s0, v253, 18
	s_nop 1
	v_add3_u32 v127, v2, v3, s0
	s_lshl_b32 s0, s95, 18
	v_lshlrev_b64 v[2:3], 7, v[194:195]
	s_add_u32 s0, s6, s0
	v_lshl_add_u64 v[0:1], v[2:3], 0, v[0:1]
	s_addc_u32 s1, s7, 0
	v_lshl_add_u64 v[0:1], s[0:1], 0, v[0:1]
	s_mov_b64 s[0:1], 0x600000
	v_lshl_add_u64 v[92:93], v[0:1], 0, s[0:1]
	global_load_dwordx4 v[130:133], v[92:93], off
	global_load_dwordx4 v[134:137], v[92:93], off offset:32
	global_load_dwordx4 v[138:141], v[92:93], off offset:64
	global_load_dwordx4 v[142:145], v[92:93], off offset:96
	s_cmp_gt_i32 s8, s5
	s_cbranch_scc1 .Lidx_p0
	v_add_co_u32_e32 v4, vcc, 0x8000, v92
	s_nop 1
	v_addc_co_u32_e32 v5, vcc, 0, v93, vcc
	global_load_dwordx4 v[146:149], v[4:5], off
	global_load_dwordx4 v[150:153], v[4:5], off offset:32
	global_load_dwordx4 v[154:157], v[4:5], off offset:64
	global_load_dwordx4 v[158:161], v[4:5], off offset:96
.Lidx_p0:
	s_branch .LBB0_382

.LBB0_382:
	s_cmp_le_i32 s8, s5
	s_cselect_b64 s[0:1], -1, 0
	s_waitcnt vmcnt(0)
	v_mov_b64_e32 v[0:1], v[130:131]
	v_mov_b64_e32 v[2:3], v[132:133]
	v_mov_b64_e32 v[88:89], v[134:135]
	v_mov_b64_e32 v[90:91], v[136:137]
	v_mov_b64_e32 v[84:85], v[138:139]
	v_mov_b64_e32 v[86:87], v[140:141]
	v_mov_b64_e32 v[80:81], v[142:143]
	v_mov_b64_e32 v[82:83], v[144:145]
	v_mov_b64_e32 v[76:77], v[146:147]
	v_mov_b64_e32 v[78:79], v[148:149]
	v_mov_b64_e32 v[72:73], v[150:151]
	v_mov_b64_e32 v[74:75], v[152:153]
	v_mov_b64_e32 v[68:69], v[154:155]
	v_mov_b64_e32 v[70:71], v[156:157]
	v_mov_b64_e32 v[64:65], v[158:159]
	v_mov_b64_e32 v[66:67], v[160:161]
	s_add_i32 s9, s8, 16
	s_cmp_gt_u32 s9, s4
	s_cbranch_scc1 .Lidx_nopf
	s_mov_b64 s[12:13], 0x10000
	v_lshl_add_u64 v[162:163], v[92:93], 0, s[12:13]
	global_load_dwordx4 v[130:133], v[162:163], off
	global_load_dwordx4 v[134:137], v[162:163], off offset:32
	global_load_dwordx4 v[138:141], v[162:163], off offset:64
	global_load_dwordx4 v[142:145], v[162:163], off offset:96
	s_cmp_gt_i32 s9, s5
	s_cbranch_scc1 .Lidx_nopf
	v_add_co_u32_e32 v164, vcc, 0x8000, v162
	s_nop 1
	v_addc_co_u32_e32 v165, vcc, 0, v163, vcc
	global_load_dwordx4 v[146:149], v[164:165], off
	global_load_dwordx4 v[150:153], v[164:165], off offset:32
	global_load_dwordx4 v[154:157], v[164:165], off offset:64
	global_load_dwordx4 v[158:161], v[164:165], off offset:96
.Lidx_nopf:
	v_mfma_f32_32x32x16_f16 v[16:31], v[32:35], v[0:3], 0
	s_andn2_b64 vcc, exec, s[0:1]
	v_mfma_f32_32x32x16_f16 v[0:15], v[48:51], v[0:3], 0
	v_mfma_f32_32x32x16_f16 v[0:15], v[52:55], v[88:91], v[0:15]
	v_mfma_f32_32x32x16_f16 v[16:31], v[36:39], v[88:91], v[16:31]
	v_mfma_f32_32x32x16_f16 v[0:15], v[56:59], v[84:87], v[0:15]
	v_mfma_f32_32x32x16_f16 v[16:31], v[40:43], v[84:87], v[16:31]
	v_mfma_f32_32x32x16_f16 v[0:15], v[60:63], v[80:83], v[0:15]
	v_mfma_f32_32x32x16_f16 v[16:31], v[44:47], v[80:83], v[16:31]
	s_nop 10
	v_max_f32_e32 v0, v0, v0
	v_max_f32_e32 v0, 0, v0
	v_max_f32_e32 v1, v1, v1
	v_fma_f32 v0, v0, v111, 0
	v_max_f32_e32 v1, 0, v1
	v_fmac_f32_e32 v0, v1, v112
	v_max_f32_e32 v16, v16, v16
	v_max_f32_e32 v16, 0, v16
	v_max_f32_e32 v17, v17, v17
	v_fma_f32 v16, v16, v95, 0
	v_max_f32_e32 v17, 0, v17
	v_max_f32_e32 v1, v18, v18
	v_fmac_f32_e32 v16, v17, v96
	v_max_f32_e32 v1, 0, v1
	v_fmac_f32_e32 v16, v1, v97
	v_max_f32_e32 v1, v2, v2
	v_max_f32_e32 v1, 0, v1
	v_fmac_f32_e32 v0, v1, v113
	v_max_f32_e32 v1, v19, v19
	v_max_f32_e32 v1, 0, v1
	v_fmac_f32_e32 v16, v1, v98
	v_max_f32_e32 v1, v3, v3
	v_max_f32_e32 v1, 0, v1
	v_fmac_f32_e32 v0, v1, v114
	v_add_u32_e32 v1, 0xfffeff00, v127
	ds_write_b32 v1, v16
	ds_write_b32 v127, v0
	v_max_f32_e32 v0, v20, v20
	v_max_f32_e32 v0, 0, v0
	v_max_f32_e32 v2, v21, v21
	v_fma_f32 v0, v0, v99, 0
	v_max_f32_e32 v1, v4, v4
	v_max_f32_e32 v2, 0, v2
	v_max_f32_e32 v1, 0, v1
	v_fmac_f32_e32 v0, v2, v100
	v_max_f32_e32 v2, v5, v5
	v_fma_f32 v1, v1, v115, 0
	v_max_f32_e32 v2, 0, v2
	v_fmac_f32_e32 v1, v2, v116
	v_max_f32_e32 v2, v22, v22
	v_max_f32_e32 v2, 0, v2
	v_fmac_f32_e32 v0, v2, v101
	v_max_f32_e32 v2, v6, v6
	v_max_f32_e32 v2, 0, v2
	v_fmac_f32_e32 v1, v2, v117
	v_max_f32_e32 v2, v23, v23
	v_max_f32_e32 v2, 0, v2
	v_fmac_f32_e32 v0, v2, v102
	v_max_f32_e32 v2, v7, v7
	v_max_f32_e32 v2, 0, v2
	v_fmac_f32_e32 v1, v2, v118
	v_add_u32_e32 v2, 0xffff3f40, v127
	ds_write_b32 v2, v0
	ds_write_b32 v127, v1 offset:16448
	v_max_f32_e32 v0, v24, v24
	v_max_f32_e32 v0, 0, v0
	v_max_f32_e32 v2, v25, v25
	v_fma_f32 v0, v0, v103, 0
	v_max_f32_e32 v1, v8, v8
	v_max_f32_e32 v2, 0, v2
	v_max_f32_e32 v1, 0, v1
	v_fmac_f32_e32 v0, v2, v104
	v_max_f32_e32 v2, v9, v9
	v_fma_f32 v1, v1, v119, 0
	v_max_f32_e32 v2, 0, v2
	v_fmac_f32_e32 v1, v2, v120
	v_max_f32_e32 v2, v26, v26
	v_max_f32_e32 v2, 0, v2
	v_fmac_f32_e32 v0, v2, v105
	v_max_f32_e32 v2, v10, v10
	v_max_f32_e32 v2, 0, v2
	v_fmac_f32_e32 v1, v2, v121
	v_max_f32_e32 v2, v27, v27
	v_max_f32_e32 v2, 0, v2
	v_fmac_f32_e32 v0, v2, v106
	v_max_f32_e32 v2, v11, v11
	v_max_f32_e32 v2, 0, v2
	v_fmac_f32_e32 v1, v2, v122
	v_add_u32_e32 v2, 0xffff7f80, v127
	ds_write_b32 v2, v0
	ds_write_b32 v127, v1 offset:32896
	v_max_f32_e32 v0, v28, v28
	v_max_f32_e32 v0, 0, v0
	v_max_f32_e32 v2, v29, v29
	v_fma_f32 v0, v0, v107, 0
	v_max_f32_e32 v1, v12, v12
	v_max_f32_e32 v2, 0, v2
	v_max_f32_e32 v1, 0, v1
	v_fmac_f32_e32 v0, v2, v108
	v_max_f32_e32 v2, v13, v13
	v_fma_f32 v1, v1, v123, 0
	v_max_f32_e32 v2, 0, v2
	v_fmac_f32_e32 v1, v2, v124
	v_max_f32_e32 v2, v30, v30
	v_max_f32_e32 v2, 0, v2
	v_fmac_f32_e32 v0, v2, v109
	v_max_f32_e32 v2, v14, v14
	v_max_f32_e32 v2, 0, v2
	v_fmac_f32_e32 v1, v2, v125
	v_max_f32_e32 v2, v31, v31
	v_max_f32_e32 v2, 0, v2
	v_fmac_f32_e32 v0, v2, v110
	v_max_f32_e32 v2, v15, v15
	v_max_f32_e32 v2, 0, v2
	v_fmac_f32_e32 v1, v2, v126
	v_add_u32_e32 v2, 0xffffbfc0, v127
	ds_write_b32 v2, v0
	ds_write_b32 v127, v1 offset:49344
	s_cbranch_vccnz .LBB0_381
	v_mfma_f32_32x32x16_f16 v[0:15], v[48:51], v[76:79], 0
	v_mfma_f32_32x32x16_f16 v[16:31], v[32:35], v[76:79], 0
	v_mfma_f32_32x32x16_f16 v[0:15], v[52:55], v[72:75], v[0:15]
	v_mfma_f32_32x32x16_f16 v[16:31], v[36:39], v[72:75], v[16:31]
	v_mfma_f32_32x32x16_f16 v[0:15], v[56:59], v[68:71], v[0:15]
	v_mfma_f32_32x32x16_f16 v[16:31], v[40:43], v[68:71], v[16:31]
	v_mfma_f32_32x32x16_f16 v[0:15], v[60:63], v[64:67], v[0:15]
	v_mfma_f32_32x32x16_f16 v[16:31], v[44:47], v[64:67], v[16:31]
	s_nop 10
	v_max_f32_e32 v0, v0, v0
	v_max_f32_e32 v0, 0, v0
	v_max_f32_e32 v1, v1, v1
	v_fma_f32 v0, v0, v111, 0
	v_max_f32_e32 v1, 0, v1
	v_fmac_f32_e32 v0, v1, v112
	v_max_f32_e32 v16, v16, v16
	v_max_f32_e32 v16, 0, v16
	v_max_f32_e32 v17, v17, v17
	v_fma_f32 v16, v16, v95, 0
	v_max_f32_e32 v17, 0, v17
	v_max_f32_e32 v1, v18, v18
	v_fmac_f32_e32 v16, v17, v96
	v_max_f32_e32 v1, 0, v1
	v_fmac_f32_e32 v16, v1, v97
	v_max_f32_e32 v1, v2, v2
	v_max_f32_e32 v1, 0, v1
	v_fmac_f32_e32 v0, v1, v113
	v_max_f32_e32 v1, v19, v19
	v_max_f32_e32 v1, 0, v1
	v_fmac_f32_e32 v16, v1, v98
	v_max_f32_e32 v1, v3, v3
	v_max_f32_e32 v1, 0, v1
	v_fmac_f32_e32 v0, v1, v114
	v_add_u32_e32 v1, 0xffff0300, v127
	ds_write_b32 v1, v16
	ds_write_b32 v127, v0 offset:1024
	v_max_f32_e32 v0, v20, v20
	v_max_f32_e32 v0, 0, v0
	v_max_f32_e32 v2, v21, v21
	v_fma_f32 v0, v0, v99, 0
	v_max_f32_e32 v1, v4, v4
	v_max_f32_e32 v2, 0, v2
	v_max_f32_e32 v1, 0, v1
	v_fmac_f32_e32 v0, v2, v100
	v_max_f32_e32 v2, v5, v5
	v_fma_f32 v1, v1, v115, 0
	v_max_f32_e32 v2, 0, v2
	v_fmac_f32_e32 v1, v2, v116
	v_max_f32_e32 v2, v22, v22
	v_max_f32_e32 v2, 0, v2
	v_fmac_f32_e32 v0, v2, v101
	v_max_f32_e32 v2, v6, v6
	v_max_f32_e32 v2, 0, v2
	v_fmac_f32_e32 v1, v2, v117
	v_max_f32_e32 v2, v23, v23
	v_max_f32_e32 v2, 0, v2
	v_fmac_f32_e32 v0, v2, v102
	v_max_f32_e32 v2, v7, v7
	v_max_f32_e32 v2, 0, v2
	v_fmac_f32_e32 v1, v2, v118
	v_add_u32_e32 v2, 0xffff4340, v127
	ds_write_b32 v2, v0
	ds_write_b32 v127, v1 offset:17472
	v_max_f32_e32 v0, v24, v24
	v_max_f32_e32 v0, 0, v0
	v_max_f32_e32 v2, v25, v25
	v_fma_f32 v0, v0, v103, 0
	v_max_f32_e32 v1, v8, v8
	v_max_f32_e32 v2, 0, v2
	v_max_f32_e32 v1, 0, v1
	v_fmac_f32_e32 v0, v2, v104
	v_max_f32_e32 v2, v9, v9
	v_fma_f32 v1, v1, v119, 0
	v_max_f32_e32 v2, 0, v2
	v_fmac_f32_e32 v1, v2, v120
	v_max_f32_e32 v2, v26, v26
	v_max_f32_e32 v2, 0, v2
	v_fmac_f32_e32 v0, v2, v105
	v_max_f32_e32 v2, v10, v10
	v_max_f32_e32 v2, 0, v2
	v_fmac_f32_e32 v1, v2, v121
	v_max_f32_e32 v2, v27, v27
	v_max_f32_e32 v2, 0, v2
	v_fmac_f32_e32 v0, v2, v106
	v_max_f32_e32 v2, v11, v11
	v_max_f32_e32 v2, 0, v2
	v_fmac_f32_e32 v1, v2, v122
	v_add_u32_e32 v2, 0xffff8380, v127
	ds_write_b32 v2, v0
	ds_write_b32 v127, v1 offset:33920
	v_max_f32_e32 v0, v28, v28
	v_max_f32_e32 v0, 0, v0
	v_max_f32_e32 v2, v29, v29
	v_fma_f32 v0, v0, v107, 0
	v_max_f32_e32 v1, v12, v12
	v_max_f32_e32 v2, 0, v2
	v_max_f32_e32 v1, 0, v1
	v_fmac_f32_e32 v0, v2, v108
	v_max_f32_e32 v2, v13, v13
	v_fma_f32 v1, v1, v123, 0
	v_max_f32_e32 v2, 0, v2
	v_fmac_f32_e32 v1, v2, v124
	v_max_f32_e32 v2, v30, v30
	v_max_f32_e32 v2, 0, v2
	v_fmac_f32_e32 v0, v2, v109
	v_max_f32_e32 v2, v14, v14
	v_max_f32_e32 v2, 0, v2
	v_fmac_f32_e32 v1, v2, v125
	v_max_f32_e32 v2, v31, v31
	v_max_f32_e32 v2, 0, v2
	v_fmac_f32_e32 v0, v2, v110
	v_max_f32_e32 v2, v15, v15
	v_max_f32_e32 v2, 0, v2
	v_fmac_f32_e32 v1, v2, v126
	v_add_u32_e32 v2, 0xffffc3c0, v127
	ds_write_b32 v2, v0
	ds_write_b32 v127, v1 offset:50368
	s_branch .LBB0_381

.LBB0_1274:
	v_bfe_u32 v7, v125, 5, 1
	v_lshlrev_b32_e32 v8, 2, v7
	s_movk_i32 s0, 0x100
	v_lshlrev_b32_e64 v110, v8, s0
	s_movk_i32 s0, 0x200
	v_lshlrev_b32_e64 v111, v8, s0
	s_movk_i32 s0, 0x400
	v_lshlrev_b32_e64 v112, v8, s0
	s_movk_i32 s0, 0x800
	v_lshlrev_b32_e64 v113, v8, s0
	s_mov_b32 s0, 0x10000
	v_lshlrev_b32_e64 v114, v8, s0
	s_mov_b32 s0, 0x20000
	v_lshlrev_b32_e64 v115, v8, s0
	s_mov_b32 s0, 0x40000
	v_lshlrev_b32_e64 v116, v8, s0
	s_mov_b32 s0, 0x80000
	v_and_b32_e32 v6, 31, v125
	v_lshlrev_b32_e64 v117, v8, s0
	s_mov_b32 s0, 0x1000000
	v_readlane_b32 s8, v253, 41
	v_lshlrev_b32_e64 v118, v8, s0
	s_brev_b32 s0, 64
	v_mad_u32_u24 v122, v6, s81, 16
	v_readlane_b32 s9, v253, 42
	v_and_b32_e32 v6, 7, v125
	v_lshlrev_b32_e32 v104, 4, v7
	v_lshlrev_b32_e32 v105, 3, v7
	v_lshlrev_b32_e64 v119, v8, s0
	s_brev_b32 s0, 32
	v_lshl_add_u64 v[4:5], s[8:9], 0, v[4:5]
	v_lshlrev_b32_e32 v6, 4, v6
	v_mov_b32_e32 v7, v195
	v_lshlrev_b32_e64 v120, v8, s0
	s_brev_b32 s0, 16
	v_lshl_add_u64 v[4:5], v[4:5], 0, v[6:7]
	v_lshl_add_u64 v[2:3], s[8:9], 0, v[2:3]
	v_lshlrev_b32_e64 v121, v8, s0
	v_lshl_add_u64 v[4:5], s[76:77], 0, v[4:5]
	s_mov_b64 s[0:1], 0x404000
	v_lshl_add_u64 v[2:3], v[2:3], 0, v[6:7]
	v_lshl_add_u64 v[94:95], v[4:5], 0, s[0:1]
	v_lshl_add_u64 v[2:3], s[76:77], 0, v[2:3]
	s_mov_b64 s[0:1], 0xc00100
	v_lshl_add_u64 v[96:97], v[2:3], 0, s[0:1]
	s_mov_b64 s[0:1], 0x1200010
	v_mov_b32_e32 v14, v195
	v_mov_b32_e32 v15, v195
	v_lshlrev_b32_e64 v106, v8, 1
	v_lshlrev_b32_e64 v107, v8, 2
	v_lshlrev_b32_e64 v108, v8, 4
	v_lshlrev_b32_e64 v109, v8, 8
	v_lshl_add_u64 v[98:99], v[0:1], 0, s[0:1]
	v_mov_b32_e32 v0, v195
	v_mov_b32_e32 v1, v195
	v_mov_b32_e32 v2, v195
	v_mov_b32_e32 v3, v195
	v_mov_b32_e32 v4, v195
	v_mov_b32_e32 v5, v195
	v_mov_b32_e32 v6, v195
	v_mov_b32_e32 v8, v195
	v_mov_b32_e32 v9, v195
	v_mov_b32_e32 v10, v195
	v_mov_b32_e32 v11, v195
	v_mov_b32_e32 v12, v195
	v_mov_b32_e32 v13, v195
	v_mov_b64_e32 v[30:31], v[14:15]
	s_lshr_b32 s4, s80, 3
	s_mov_b32 s5, 0
	v_mov_b32_e32 v100, 0xf149f2ca
	v_mov_b32_e32 v126, 0
	v_mov_b32_e32 v123, 0
	v_mov_b64_e32 v[28:29], v[12:13]
	v_mov_b64_e32 v[26:27], v[10:11]
	v_mov_b64_e32 v[24:25], v[8:9]
	v_mov_b64_e32 v[22:23], v[6:7]
	v_mov_b64_e32 v[20:21], v[4:5]
	v_mov_b64_e32 v[18:19], v[2:3]
	v_mov_b64_e32 v[16:17], v[0:1]
	v_lshrrev_b32_e32 v144, 1, v105
	s_waitcnt lgkmcnt(0)
	s_barrier
.LBB0_1275:
	s_movk_i32 s0, 0x4800
	v_mul_lo_u32 v32, v123, s0
	v_add_u32_e32 v130, v122, v32
	v_add_u32_e32 v127, v130, v104
	ds_read_b128 v[32:35], v127 offset:32768
	ds_read_b128 v[132:135], v127 offset:32800
	v_cmp_ne_u32_e32 vcc, -1, v102
	v_cmp_ne_u32_e64 s[0:1], -1, v103
	s_waitcnt lgkmcnt(1)
	v_mfma_f32_32x32x16_f16 v[48:63], v[32:35], v[72:75], 0
	ds_read_b128 v[32:35], v127 offset:37376
	s_waitcnt lgkmcnt(1)
	v_mfma_f32_32x32x16_f16 v[48:63], v[132:135], v[64:67], v[48:63]
	ds_read_b128 v[132:135], v127 offset:37408
	s_waitcnt lgkmcnt(1)
	v_mfma_f32_32x32x16_f16 v[32:47], v[32:35], v[72:75], 0
	s_waitcnt lgkmcnt(0)
	v_mfma_f32_32x32x16_f16 v[32:47], v[132:135], v[64:67], v[32:47]
	ds_read_b128 v[132:135], v127 offset:32832
	s_waitcnt lgkmcnt(0)
	v_mfma_f32_32x32x16_f16 v[48:63], v[132:135], v[68:71], v[48:63]
	ds_read_b128 v[132:135], v127 offset:37440
	s_waitcnt lgkmcnt(0)
	v_mfma_f32_32x32x16_f16 v[32:47], v[132:135], v[68:71], v[32:47]
	ds_read_b128 v[132:135], v127 offset:32864
	s_waitcnt lgkmcnt(0)
	v_mfma_f32_32x32x16_f16 v[48:63], v[132:135], v[76:79], v[48:63]
	ds_read_b128 v[132:135], v127 offset:37472
	s_waitcnt lgkmcnt(0)
	v_mfma_f32_32x32x16_f16 v[32:47], v[132:135], v[76:79], v[32:47]
	s_cbranch_vccz .LBB0_1277
	v_lshrrev_b32_e32 v145, v144, v102
	v_bfe_i32 v146, v145, 0, 1
	v_bfe_i32 v147, v145, 1, 1
	v_bfe_i32 v148, v145, 2, 1
	v_bfe_i32 v149, v145, 3, 1
	v_bfe_i32 v150, v145, 8, 1
	v_bfe_i32 v151, v145, 9, 1
	v_bfe_i32 v152, v145, 10, 1
	v_bfe_i32 v153, v145, 11, 1
	v_bfe_i32 v154, v145, 16, 1
	v_bfe_i32 v155, v145, 17, 1
	v_bfe_i32 v156, v145, 18, 1
	v_bfe_i32 v157, v145, 19, 1
	v_bfe_i32 v158, v145, 24, 1
	v_bfe_i32 v159, v145, 25, 1
	v_bfe_i32 v160, v145, 26, 1
	v_bfe_i32 v161, v145, 27, 1
	v_bfi_b32 v48, v146, v48, v193
	v_bfi_b32 v49, v147, v49, v193
	v_bfi_b32 v50, v148, v50, v193
	v_bfi_b32 v51, v149, v51, v193
	v_bfi_b32 v52, v150, v52, v193
	v_bfi_b32 v53, v151, v53, v193
	v_bfi_b32 v54, v152, v54, v193
	v_bfi_b32 v55, v153, v55, v193
	v_bfi_b32 v56, v154, v56, v193
	v_bfi_b32 v57, v155, v57, v193
	v_bfi_b32 v58, v156, v58, v193
	v_bfi_b32 v59, v157, v59, v193
	v_bfi_b32 v60, v158, v60, v193
	v_bfi_b32 v61, v159, v61, v193
	v_bfi_b32 v62, v160, v62, v193
	v_bfi_b32 v63, v161, v63, v193
.LBB0_1277:
	s_cmp_eq_u64 s[0:1], 0
	s_cbranch_scc1 .LBB0_1279
	v_lshrrev_b32_e32 v145, v144, v103
	v_bfe_i32 v146, v145, 0, 1
	v_bfe_i32 v147, v145, 1, 1
	v_bfe_i32 v148, v145, 2, 1
	v_bfe_i32 v149, v145, 3, 1
	v_bfe_i32 v150, v145, 8, 1
	v_bfe_i32 v151, v145, 9, 1
	v_bfe_i32 v152, v145, 10, 1
	v_bfe_i32 v153, v145, 11, 1
	v_bfe_i32 v154, v145, 16, 1
	v_bfe_i32 v155, v145, 17, 1
	v_bfe_i32 v156, v145, 18, 1
	v_bfe_i32 v157, v145, 19, 1
	v_bfe_i32 v158, v145, 24, 1
	v_bfe_i32 v159, v145, 25, 1
	v_bfe_i32 v160, v145, 26, 1
	v_bfe_i32 v161, v145, 27, 1
	v_bfi_b32 v32, v146, v32, v193
	v_bfi_b32 v33, v147, v33, v193
	v_bfi_b32 v34, v148, v34, v193
	v_bfi_b32 v35, v149, v35, v193
	v_bfi_b32 v36, v150, v36, v193
	v_bfi_b32 v37, v151, v37, v193
	v_bfi_b32 v38, v152, v38, v193
	v_bfi_b32 v39, v153, v39, v193
	v_bfi_b32 v40, v154, v40, v193
	v_bfi_b32 v41, v155, v41, v193
	v_bfi_b32 v42, v156, v42, v193
	v_bfi_b32 v43, v157, v43, v193
	v_bfi_b32 v44, v158, v44, v193
	v_bfi_b32 v45, v159, v45, v193
	v_bfi_b32 v46, v160, v46, v193
	v_bfi_b32 v47, v161, v47, v193
.LBB0_1279:
	s_nop 8
	s_mov_b32 s0, 0xf149f2ca
	v_max3_f32 v102, v48, v32, s0
	v_max3_f32 v102, v102, v49, v33
	v_max3_f32 v102, v102, v50, v34
	v_max3_f32 v102, v102, v51, v35
	v_max3_f32 v102, v102, v52, v36
	v_max3_f32 v102, v102, v53, v37
	v_max3_f32 v102, v102, v54, v38
	v_max3_f32 v102, v102, v55, v39
	v_max3_f32 v102, v102, v56, v40
	v_max3_f32 v102, v102, v57, v41
	v_max3_f32 v102, v102, v58, v42
	v_max3_f32 v102, v102, v59, v43
	v_max3_f32 v102, v102, v60, v44
	v_max3_f32 v102, v102, v61, v45
	v_max3_f32 v102, v102, v62, v46
	v_max3_f32 v102, v102, v63, v47
	v_mov_b32_e32 v103, v192
	s_nop 0
	v_lshlrev_b32_e32 v103, 2, v103
	v_xor_b32_e32 v103, 0x80, v103
	ds_bpermute_b32 v103, v103, v102
	s_waitcnt lgkmcnt(0)
	v_max3_f32 v127, v100, v102, v103
	v_sub_f32_e32 v100, v100, v127
	v_exp_f32_e32 v100, v100
	s_nop 0
	v_cmp_neq_f32_e32 vcc, 1.0, v100
	s_cbranch_vccz .LBB0_1281
	v_pk_mul_f32 v[30:31], v[30:31], v[100:101] op_sel_hi:[1,0]
	v_pk_mul_f32 v[28:29], v[28:29], v[100:101] op_sel_hi:[1,0]
	v_pk_mul_f32 v[26:27], v[26:27], v[100:101] op_sel_hi:[1,0]
	v_pk_mul_f32 v[24:25], v[24:25], v[100:101] op_sel_hi:[1,0]
	v_pk_mul_f32 v[22:23], v[22:23], v[100:101] op_sel_hi:[1,0]
	v_pk_mul_f32 v[20:21], v[20:21], v[100:101] op_sel_hi:[1,0]
	v_pk_mul_f32 v[18:19], v[18:19], v[100:101] op_sel_hi:[1,0]
	v_pk_mul_f32 v[16:17], v[16:17], v[100:101] op_sel_hi:[1,0]
	v_pk_mul_f32 v[14:15], v[14:15], v[100:101] op_sel_hi:[1,0]
	v_pk_mul_f32 v[12:13], v[12:13], v[100:101] op_sel_hi:[1,0]
	v_pk_mul_f32 v[10:11], v[10:11], v[100:101] op_sel_hi:[1,0]
	v_pk_mul_f32 v[8:9], v[8:9], v[100:101] op_sel_hi:[1,0]
	v_pk_mul_f32 v[6:7], v[6:7], v[100:101] op_sel_hi:[1,0]
	v_pk_mul_f32 v[4:5], v[4:5], v[100:101] op_sel_hi:[1,0]
	v_pk_mul_f32 v[2:3], v[2:3], v[100:101] op_sel_hi:[1,0]
	v_pk_mul_f32 v[0:1], v[0:1], v[100:101] op_sel_hi:[1,0]
.LBB0_1281:
	v_mov_b32_e32 v162, v127
	v_pk_add_f32 v[48:49], v[48:49], v[162:163] op_sel_hi:[1,0] neg_lo:[0,1] neg_hi:[0,1]
	v_pk_add_f32 v[50:51], v[50:51], v[162:163] op_sel_hi:[1,0] neg_lo:[0,1] neg_hi:[0,1]
	v_pk_add_f32 v[52:53], v[52:53], v[162:163] op_sel_hi:[1,0] neg_lo:[0,1] neg_hi:[0,1]
	v_pk_add_f32 v[54:55], v[54:55], v[162:163] op_sel_hi:[1,0] neg_lo:[0,1] neg_hi:[0,1]
	v_pk_add_f32 v[56:57], v[56:57], v[162:163] op_sel_hi:[1,0] neg_lo:[0,1] neg_hi:[0,1]
	v_pk_add_f32 v[58:59], v[58:59], v[162:163] op_sel_hi:[1,0] neg_lo:[0,1] neg_hi:[0,1]
	v_pk_add_f32 v[60:61], v[60:61], v[162:163] op_sel_hi:[1,0] neg_lo:[0,1] neg_hi:[0,1]
	v_pk_add_f32 v[62:63], v[62:63], v[162:163] op_sel_hi:[1,0] neg_lo:[0,1] neg_hi:[0,1]
	v_pk_add_f32 v[32:33], v[32:33], v[162:163] op_sel_hi:[1,0] neg_lo:[0,1] neg_hi:[0,1]
	v_pk_add_f32 v[34:35], v[34:35], v[162:163] op_sel_hi:[1,0] neg_lo:[0,1] neg_hi:[0,1]
	v_pk_add_f32 v[36:37], v[36:37], v[162:163] op_sel_hi:[1,0] neg_lo:[0,1] neg_hi:[0,1]
	v_pk_add_f32 v[38:39], v[38:39], v[162:163] op_sel_hi:[1,0] neg_lo:[0,1] neg_hi:[0,1]
	v_pk_add_f32 v[40:41], v[40:41], v[162:163] op_sel_hi:[1,0] neg_lo:[0,1] neg_hi:[0,1]
	v_pk_add_f32 v[42:43], v[42:43], v[162:163] op_sel_hi:[1,0] neg_lo:[0,1] neg_hi:[0,1]
	v_pk_add_f32 v[44:45], v[44:45], v[162:163] op_sel_hi:[1,0] neg_lo:[0,1] neg_hi:[0,1]
	v_pk_add_f32 v[46:47], v[46:47], v[162:163] op_sel_hi:[1,0] neg_lo:[0,1] neg_hi:[0,1]
	v_exp_f32_e32 v128, v32
	v_exp_f32_e32 v129, v33
	v_exp_f32_e32 v34, v34
	v_exp_f32_e32 v35, v35
	v_exp_f32_e32 v36, v36
	v_exp_f32_e32 v37, v37
	v_exp_f32_e32 v38, v38
	v_exp_f32_e32 v39, v39
	v_exp_f32_e32 v40, v40
	v_exp_f32_e32 v41, v41
	v_exp_f32_e32 v42, v42
	v_exp_f32_e32 v43, v43
	v_exp_f32_e32 v44, v44
	v_exp_f32_e32 v45, v45
	v_exp_f32_e32 v46, v46
	v_exp_f32_e32 v47, v47
	v_exp_f32_e32 v48, v48
	v_exp_f32_e32 v49, v49
	v_exp_f32_e32 v50, v50
	v_exp_f32_e32 v51, v51
	v_exp_f32_e32 v52, v52
	v_exp_f32_e32 v53, v53
	v_exp_f32_e32 v54, v54
	v_exp_f32_e32 v55, v55
	v_exp_f32_e32 v56, v56
	v_exp_f32_e32 v57, v57
	v_exp_f32_e32 v58, v58
	v_exp_f32_e32 v59, v59
	v_exp_f32_e32 v60, v60
	v_exp_f32_e32 v61, v61
	v_exp_f32_e32 v62, v62
	v_exp_f32_e32 v63, v63
	v_add_u32_e32 v32, v130, v105
	v_add_u32_e32 v33, 0xa000, v32
	ds_read2_b64 v[136:139], v33 offset0:128 offset1:130
	ds_read2_b64 v[140:143], v33 offset0:132 offset1:134
	v_cvt_pkrtz_f16_f32 v133, v50, v51
	v_cvt_pkrtz_f16_f32 v132, v48, v49
	v_cvt_pkrtz_f16_f32 v134, v52, v53
	v_cvt_pkrtz_f16_f32 v135, v54, v55
	v_add_u32_e32 v32, 0xb000, v32
	s_mov_b64 s[0:1], -1
	s_waitcnt lgkmcnt(1)
	v_mfma_f32_32x32x16_f16 v[16:31], v[136:139], v[132:135], v[16:31]
	ds_read2_b64 v[136:139], v32 offset0:192 offset1:194
	s_cmp_eq_u32 s4, s5
	s_waitcnt lgkmcnt(0)
	v_mfma_f32_32x32x16_f16 v[0:15], v[136:139], v[132:135], v[0:15]
	ds_read2_b64 v[136:139], v32 offset0:196 offset1:198
	v_cvt_pkrtz_f16_f32 v132, v56, v57
	v_cvt_pkrtz_f16_f32 v133, v58, v59
	v_cvt_pkrtz_f16_f32 v134, v60, v61
	v_cvt_pkrtz_f16_f32 v135, v62, v63
	s_waitcnt lgkmcnt(0)
	s_nop 0
	v_mfma_f32_32x32x16_f16 v[0:15], v[136:139], v[132:135], v[0:15]
	ds_read2_b64 v[136:139], v33 offset0:136 offset1:138
	v_mfma_f32_32x32x16_f16 v[16:31], v[140:143], v[132:135], v[16:31]
	v_cvt_pkrtz_f16_f32 v132, v128, v129
	v_cvt_pkrtz_f16_f32 v133, v34, v35
	v_cvt_pkrtz_f16_f32 v134, v36, v37
	v_cvt_pkrtz_f16_f32 v135, v38, v39
	s_waitcnt lgkmcnt(0)
	s_nop 0
	v_mfma_f32_32x32x16_f16 v[16:31], v[136:139], v[132:135], v[16:31]
	ds_read2_b64 v[136:139], v32 offset0:200 offset1:202
	s_waitcnt lgkmcnt(0)
	v_mfma_f32_32x32x16_f16 v[0:15], v[136:139], v[132:135], v[0:15]
	ds_read2_b64 v[136:139], v33 offset0:140 offset1:142
	v_cvt_pkrtz_f16_f32 v132, v40, v41
	v_cvt_pkrtz_f16_f32 v133, v42, v43
	v_cvt_pkrtz_f16_f32 v134, v44, v45
	v_cvt_pkrtz_f16_f32 v135, v46, v47
	s_waitcnt lgkmcnt(0)
	s_nop 0
	v_mfma_f32_32x32x16_f16 v[16:31], v[136:139], v[132:135], v[16:31]
	ds_read2_b64 v[136:139], v32 offset0:204 offset1:206
	s_waitcnt lgkmcnt(0)
	v_mfma_f32_32x32x16_f16 v[0:15], v[136:139], v[132:135], v[0:15]
	s_nop 11
	v_readfirstlane_b32 s8, v0
	s_cbranch_scc1 .LBB0_1285
	v_xor_b32_e32 v123, 1, v123
	s_movk_i32 s0, 0x4800
	v_mul_lo_u32 v32, v123, s0
	s_add_i32 s8, s5, 1
	v_add_u32_e32 v32, v89, v32
	s_waitcnt vmcnt(2)
	ds_write_b128 v32, v[80:83] offset:32768
	s_waitcnt vmcnt(1)
	ds_write_b128 v32, v[84:87] offset:41984
	s_cmp_ge_u32 s8, s4
	s_waitcnt vmcnt(0)
	v_mov_b64_e32 v[32:33], v[92:93]
	s_cbranch_scc1 .LBB0_1284
	global_load_dwordx4 v[80:83], v[94:95], off
	global_load_dwordx4 v[84:87], v[96:97], off
	global_load_dwordx2 v[32:33], v[98:99], off
